# GEMM main loops: the redundant second lgkmcnt(0) after each pre-MFMA barrier removed (own LDS reads are already waited for before the barrier)
# speedup vs baseline: 1.0012x; 1.0012x over previous
.LBB0_264:
	s_add_i32 s22, s84, 2
	s_add_u32 s0, s82, 0x80
	s_addc_u32 s1, s83, 0
	s_add_i32 s30, 0, 0x10000
	s_cmp_eq_u32 s57, s84
	s_cselect_b32 s85, s45, s1
	s_cselect_b32 s84, s44, s0
	v_add_u32_e32 v154, s30, v139
	s_cselect_b32 s1, s81, vcc_hi
	s_cselect_b32 s0, s80, vcc_lo
	s_add_i32 s86, 0, 0x14000
	ds_read_b128 v[130:133], v154
	ds_read_b128 v[150:153], v154 offset:1024
	ds_read_b128 v[162:165], v154 offset:2048
	ds_read_b128 v[166:169], v154 offset:3072
	v_add_u32_e32 v154, s86, v139
	ds_read_b128 v[194:197], v154
	ds_read_b128 v[198:201], v154 offset:1024
	ds_read_b128 v[202:205], v154 offset:2048
	ds_read_b128 v[206:209], v154 offset:3072
	v_lshl_add_u64 v[154:155], s[82:83], 0, v[146:147]
	s_add_i32 m0, s91, 0xc000
	ds_read_b128 v[210:213], v160
	ds_read_b128 v[214:217], v160 offset:1024
	ds_read_b128 v[218:221], v160 offset:2048
	ds_read_b128 v[222:225], v160 offset:3072
	ds_read_b128 v[226:229], v160 offset:4096
	ds_read_b128 v[230:233], v160 offset:5120
	ds_read_b128 v[234:237], v160 offset:6144
	ds_read_b128 v[238:241], v160 offset:7168
	global_load_lds_dwordx4 v[154:155], off
	v_lshl_add_u64 v[154:155], s[82:83], 0, v[148:149]
	s_add_i32 m0, s91, 0xe000
	s_nop 0
	global_load_lds_dwordx4 v[154:155], off
	s_waitcnt vmcnt(8)
	s_waitcnt lgkmcnt(0)
	s_barrier
	v_mfma_f32_16x16x32_bf16 v[126:129], v[130:133], v[210:213], v[126:129]
	v_mfma_f32_16x16x32_bf16 v[122:125], v[162:165], v[210:213], v[122:125]
	v_mfma_f32_16x16x32_bf16 v[110:113], v[130:133], v[218:221], v[110:113]
	v_mfma_f32_16x16x32_bf16 v[106:109], v[162:165], v[218:221], v[106:109]
	v_mfma_f32_16x16x32_bf16 v[94:97], v[130:133], v[226:229], v[94:97]
	v_mfma_f32_16x16x32_bf16 v[90:93], v[162:165], v[226:229], v[90:93]
	v_mfma_f32_16x16x32_bf16 v[78:81], v[130:133], v[234:237], v[78:81]
	v_mfma_f32_16x16x32_bf16 v[74:77], v[162:165], v[234:237], v[74:77]
	v_mfma_f32_16x16x32_bf16 v[126:129], v[150:153], v[214:217], v[126:129]
	v_mfma_f32_16x16x32_bf16 v[122:125], v[166:169], v[214:217], v[122:125]
	v_mfma_f32_16x16x32_bf16 v[110:113], v[150:153], v[222:225], v[110:113]
	v_mfma_f32_16x16x32_bf16 v[106:109], v[166:169], v[222:225], v[106:109]
	v_mfma_f32_16x16x32_bf16 v[94:97], v[150:153], v[230:233], v[94:97]
	v_mfma_f32_16x16x32_bf16 v[90:93], v[166:169], v[230:233], v[90:93]
	v_mfma_f32_16x16x32_bf16 v[78:81], v[150:153], v[238:241], v[78:81]
	v_mfma_f32_16x16x32_bf16 v[74:77], v[166:169], v[238:241], v[74:77]
	v_mfma_f32_16x16x32_bf16 v[118:121], v[194:197], v[210:213], v[118:121]
	v_mfma_f32_16x16x32_bf16 v[114:117], v[202:205], v[210:213], v[114:117]
	v_mfma_f32_16x16x32_bf16 v[102:105], v[194:197], v[218:221], v[102:105]
	v_mfma_f32_16x16x32_bf16 v[98:101], v[202:205], v[218:221], v[98:101]
	v_mfma_f32_16x16x32_bf16 v[86:89], v[194:197], v[226:229], v[86:89]
	v_mfma_f32_16x16x32_bf16 v[82:85], v[202:205], v[226:229], v[82:85]
	v_mfma_f32_16x16x32_bf16 v[70:73], v[194:197], v[234:237], v[70:73]
	v_mfma_f32_16x16x32_bf16 v[66:69], v[202:205], v[234:237], v[66:69]
	v_mfma_f32_16x16x32_bf16 v[118:121], v[198:201], v[214:217], v[118:121]
	v_mfma_f32_16x16x32_bf16 v[114:117], v[206:209], v[214:217], v[114:117]
	v_mfma_f32_16x16x32_bf16 v[102:105], v[198:201], v[222:225], v[102:105]
	v_mfma_f32_16x16x32_bf16 v[98:101], v[206:209], v[222:225], v[98:101]
	v_mfma_f32_16x16x32_bf16 v[86:89], v[198:201], v[230:233], v[86:89]
	v_mfma_f32_16x16x32_bf16 v[82:85], v[206:209], v[230:233], v[82:85]
	v_mfma_f32_16x16x32_bf16 v[70:73], v[198:201], v[238:241], v[70:73]
	v_mfma_f32_16x16x32_bf16 v[66:69], v[206:209], v[238:241], v[66:69]
	s_barrier
	s_add_i32 s30, s30, s99
	v_lshl_add_u64 v[154:155], s[0:1], 0, v[32:33]
	s_mov_b32 m0, s30
	ds_read_b128 v[210:213], v160 offset:16384
	ds_read_b128 v[214:217], v160 offset:17408
	ds_read_b128 v[218:221], v160 offset:18432
	ds_read_b128 v[222:225], v160 offset:19456
	ds_read_b128 v[226:229], v160 offset:20480
	ds_read_b128 v[230:233], v160 offset:21504
	ds_read_b128 v[234:237], v160 offset:22528
	ds_read_b128 v[238:241], v160 offset:23552
	global_load_lds_dwordx4 v[154:155], off
	s_add_i32 m0, s30, 0x2000
	v_lshl_add_u64 v[158:159], s[0:1], 0, v[144:145]
	s_add_u32 s0, s0, s66
	s_addc_u32 s1, s1, s67
	s_add_i32 s30, s86, s99
	global_load_lds_dwordx4 v[158:159], off
	v_lshl_add_u64 v[242:243], s[0:1], 0, v[32:33]
	s_mov_b32 m0, s30
	v_lshl_add_u64 v[244:245], s[0:1], 0, v[144:145]
	global_load_lds_dwordx4 v[242:243], off
	s_add_i32 m0, s30, 0x2000
	v_lshl_add_u64 v[246:247], s[84:85], 0, v[140:141]
	global_load_lds_dwordx4 v[244:245], off
	s_mov_b32 m0, s91
	v_lshl_add_u64 v[248:249], s[84:85], 0, v[142:143]
	global_load_lds_dwordx4 v[246:247], off
	s_mov_b32 m0, s20
	s_nop 0
	global_load_lds_dwordx4 v[248:249], off
	s_waitcnt vmcnt(8)
	s_waitcnt lgkmcnt(0)
	s_barrier
	v_mfma_f32_16x16x32_bf16 v[62:65], v[130:133], v[210:213], v[62:65]
	v_mfma_f32_16x16x32_bf16 v[58:61], v[162:165], v[210:213], v[58:61]
	v_mfma_f32_16x16x32_bf16 v[46:49], v[130:133], v[218:221], v[46:49]
	v_mfma_f32_16x16x32_bf16 v[42:45], v[162:165], v[218:221], v[42:45]
	v_mfma_f32_16x16x32_bf16 v[28:31], v[130:133], v[226:229], v[28:31]
	v_mfma_f32_16x16x32_bf16 v[24:27], v[162:165], v[226:229], v[24:27]
	v_mfma_f32_16x16x32_bf16 v[12:15], v[130:133], v[234:237], v[12:15]
	v_mfma_f32_16x16x32_bf16 v[8:11], v[162:165], v[234:237], v[8:11]
	v_mfma_f32_16x16x32_bf16 v[62:65], v[150:153], v[214:217], v[62:65]
	v_mfma_f32_16x16x32_bf16 v[58:61], v[166:169], v[214:217], v[58:61]
	v_mfma_f32_16x16x32_bf16 v[46:49], v[150:153], v[222:225], v[46:49]
	v_mfma_f32_16x16x32_bf16 v[42:45], v[166:169], v[222:225], v[42:45]
	v_mfma_f32_16x16x32_bf16 v[28:31], v[150:153], v[230:233], v[28:31]
	v_mfma_f32_16x16x32_bf16 v[24:27], v[166:169], v[230:233], v[24:27]
	v_mfma_f32_16x16x32_bf16 v[12:15], v[150:153], v[238:241], v[12:15]
	v_mfma_f32_16x16x32_bf16 v[8:11], v[166:169], v[238:241], v[8:11]
	v_mfma_f32_16x16x32_bf16 v[54:57], v[194:197], v[210:213], v[54:57]
	v_mfma_f32_16x16x32_bf16 v[50:53], v[202:205], v[210:213], v[50:53]
	v_mfma_f32_16x16x32_bf16 v[38:41], v[194:197], v[218:221], v[38:41]
	v_mfma_f32_16x16x32_bf16 v[34:37], v[202:205], v[218:221], v[34:37]
	v_mfma_f32_16x16x32_bf16 v[20:23], v[194:197], v[226:229], v[20:23]
	v_mfma_f32_16x16x32_bf16 v[16:19], v[202:205], v[226:229], v[16:19]
	v_mfma_f32_16x16x32_bf16 v[4:7], v[194:197], v[234:237], v[4:7]
	v_mfma_f32_16x16x32_bf16 v[0:3], v[202:205], v[234:237], v[0:3]
	v_mfma_f32_16x16x32_bf16 v[54:57], v[198:201], v[214:217], v[54:57]
	v_mfma_f32_16x16x32_bf16 v[50:53], v[206:209], v[214:217], v[50:53]
	v_mfma_f32_16x16x32_bf16 v[38:41], v[198:201], v[222:225], v[38:41]
	v_mfma_f32_16x16x32_bf16 v[34:37], v[206:209], v[222:225], v[34:37]
	v_mfma_f32_16x16x32_bf16 v[20:23], v[198:201], v[230:233], v[20:23]
	v_mfma_f32_16x16x32_bf16 v[16:19], v[206:209], v[230:233], v[16:19]
	v_mfma_f32_16x16x32_bf16 v[4:7], v[198:201], v[238:241], v[4:7]
	v_mfma_f32_16x16x32_bf16 v[0:3], v[206:209], v[238:241], v[0:3]
	s_barrier
	s_add_i32 s30, 0, 0x18000
	v_add_u32_e32 v156, s30, v139
	s_add_i32 s86, 0, 0x1c000
	ds_read_b128 v[130:133], v156
	ds_read_b128 v[150:153], v156 offset:1024
	ds_read_b128 v[162:165], v156 offset:2048
	ds_read_b128 v[166:169], v156 offset:3072
	v_add_u32_e32 v156, s86, v139
	ds_read_b128 v[194:197], v156
	ds_read_b128 v[198:201], v156 offset:1024
	ds_read_b128 v[202:205], v156 offset:2048
	ds_read_b128 v[206:209], v156 offset:3072
	s_add_u32 s0, s84, s66
	s_addc_u32 s1, s85, s67
	s_mov_b32 m0, s25
	v_lshl_add_u64 v[250:251], s[0:1], 0, v[140:141]
	ds_read_b128 v[210:213], v160 offset:32768
	ds_read_b128 v[214:217], v160 offset:33792
	ds_read_b128 v[218:221], v160 offset:34816
	ds_read_b128 v[222:225], v160 offset:35840
	ds_read_b128 v[226:229], v160 offset:36864
	ds_read_b128 v[230:233], v160 offset:37888
	ds_read_b128 v[234:237], v160 offset:38912
	ds_read_b128 v[238:241], v160 offset:39936
	global_load_lds_dwordx4 v[250:251], off
	v_lshl_add_u64 v[250:251], s[0:1], 0, v[142:143]
	s_mov_b32 m0, s52
	s_nop 0
	global_load_lds_dwordx4 v[250:251], off
	s_waitcnt vmcnt(8)
	s_waitcnt lgkmcnt(0)
	s_barrier
	v_mfma_f32_16x16x32_bf16 v[126:129], v[130:133], v[210:213], v[126:129]
	v_mfma_f32_16x16x32_bf16 v[122:125], v[162:165], v[210:213], v[122:125]
	v_mfma_f32_16x16x32_bf16 v[110:113], v[130:133], v[218:221], v[110:113]
	v_mfma_f32_16x16x32_bf16 v[106:109], v[162:165], v[218:221], v[106:109]
	v_mfma_f32_16x16x32_bf16 v[94:97], v[130:133], v[226:229], v[94:97]
	v_mfma_f32_16x16x32_bf16 v[90:93], v[162:165], v[226:229], v[90:93]
	v_mfma_f32_16x16x32_bf16 v[78:81], v[130:133], v[234:237], v[78:81]
	v_mfma_f32_16x16x32_bf16 v[74:77], v[162:165], v[234:237], v[74:77]
	v_mfma_f32_16x16x32_bf16 v[126:129], v[150:153], v[214:217], v[126:129]
	v_mfma_f32_16x16x32_bf16 v[122:125], v[166:169], v[214:217], v[122:125]
	v_mfma_f32_16x16x32_bf16 v[110:113], v[150:153], v[222:225], v[110:113]
	v_mfma_f32_16x16x32_bf16 v[106:109], v[166:169], v[222:225], v[106:109]
	v_mfma_f32_16x16x32_bf16 v[94:97], v[150:153], v[230:233], v[94:97]
	v_mfma_f32_16x16x32_bf16 v[90:93], v[166:169], v[230:233], v[90:93]
	v_mfma_f32_16x16x32_bf16 v[78:81], v[150:153], v[238:241], v[78:81]
	v_mfma_f32_16x16x32_bf16 v[74:77], v[166:169], v[238:241], v[74:77]
	v_mfma_f32_16x16x32_bf16 v[118:121], v[194:197], v[210:213], v[118:121]
	v_mfma_f32_16x16x32_bf16 v[114:117], v[202:205], v[210:213], v[114:117]
	v_mfma_f32_16x16x32_bf16 v[102:105], v[194:197], v[218:221], v[102:105]
	v_mfma_f32_16x16x32_bf16 v[98:101], v[202:205], v[218:221], v[98:101]
	v_mfma_f32_16x16x32_bf16 v[86:89], v[194:197], v[226:229], v[86:89]
	v_mfma_f32_16x16x32_bf16 v[82:85], v[202:205], v[226:229], v[82:85]
	v_mfma_f32_16x16x32_bf16 v[70:73], v[194:197], v[234:237], v[70:73]
	v_mfma_f32_16x16x32_bf16 v[66:69], v[202:205], v[234:237], v[66:69]
	v_mfma_f32_16x16x32_bf16 v[118:121], v[198:201], v[214:217], v[118:121]
	v_mfma_f32_16x16x32_bf16 v[114:117], v[206:209], v[214:217], v[114:117]
	v_mfma_f32_16x16x32_bf16 v[102:105], v[198:201], v[222:225], v[102:105]
	v_mfma_f32_16x16x32_bf16 v[98:101], v[206:209], v[222:225], v[98:101]
	v_mfma_f32_16x16x32_bf16 v[86:89], v[198:201], v[230:233], v[86:89]
	v_mfma_f32_16x16x32_bf16 v[82:85], v[206:209], v[230:233], v[82:85]
	v_mfma_f32_16x16x32_bf16 v[70:73], v[198:201], v[238:241], v[70:73]
	v_mfma_f32_16x16x32_bf16 v[66:69], v[206:209], v[238:241], v[66:69]
	s_barrier
	s_add_i32 s0, s30, s99
	v_lshl_add_u64 v[154:155], v[154:155], 0, s[26:27]
	s_mov_b32 m0, s0
	ds_read_b128 v[210:213], v160 offset:49152
	ds_read_b128 v[214:217], v160 offset:50176
	ds_read_b128 v[218:221], v160 offset:51200
	ds_read_b128 v[222:225], v160 offset:52224
	ds_read_b128 v[226:229], v160 offset:53248
	ds_read_b128 v[230:233], v160 offset:54272
	ds_read_b128 v[234:237], v160 offset:55296
	ds_read_b128 v[238:241], v160 offset:56320
	global_load_lds_dwordx4 v[154:155], off
	v_lshl_add_u64 v[154:155], v[158:159], 0, s[26:27]
	s_add_i32 m0, s0, 0x2000
	s_add_i32 s0, s86, s99
	global_load_lds_dwordx4 v[154:155], off
	v_lshl_add_u64 v[154:155], v[242:243], 0, s[26:27]
	s_mov_b32 m0, s0
	s_nop 0
	global_load_lds_dwordx4 v[154:155], off
	v_lshl_add_u64 v[154:155], v[244:245], 0, s[26:27]
	s_add_i32 m0, s0, 0x2000
	s_nop 0
	global_load_lds_dwordx4 v[154:155], off
	v_lshl_add_u64 v[154:155], v[246:247], 0, s[26:27]
	s_mov_b32 m0, s53
	s_nop 0
	global_load_lds_dwordx4 v[154:155], off
	v_lshl_add_u64 v[154:155], v[248:249], 0, s[26:27]
	s_mov_b32 m0, s56
	s_nop 0
	global_load_lds_dwordx4 v[154:155], off
	s_waitcnt vmcnt(8)
	s_waitcnt lgkmcnt(0)
	s_barrier
	v_mfma_f32_16x16x32_bf16 v[62:65], v[130:133], v[210:213], v[62:65]
	v_mfma_f32_16x16x32_bf16 v[58:61], v[162:165], v[210:213], v[58:61]
	v_mfma_f32_16x16x32_bf16 v[46:49], v[130:133], v[218:221], v[46:49]
	v_mfma_f32_16x16x32_bf16 v[42:45], v[162:165], v[218:221], v[42:45]
	v_mfma_f32_16x16x32_bf16 v[28:31], v[130:133], v[226:229], v[28:31]
	v_mfma_f32_16x16x32_bf16 v[24:27], v[162:165], v[226:229], v[24:27]
	v_mfma_f32_16x16x32_bf16 v[12:15], v[130:133], v[234:237], v[12:15]
	v_mfma_f32_16x16x32_bf16 v[8:11], v[162:165], v[234:237], v[8:11]
	v_mfma_f32_16x16x32_bf16 v[62:65], v[150:153], v[214:217], v[62:65]
	v_mfma_f32_16x16x32_bf16 v[58:61], v[166:169], v[214:217], v[58:61]
	v_mfma_f32_16x16x32_bf16 v[46:49], v[150:153], v[222:225], v[46:49]
	v_mfma_f32_16x16x32_bf16 v[42:45], v[166:169], v[222:225], v[42:45]
	v_mfma_f32_16x16x32_bf16 v[28:31], v[150:153], v[230:233], v[28:31]
	v_mfma_f32_16x16x32_bf16 v[24:27], v[166:169], v[230:233], v[24:27]
	v_mfma_f32_16x16x32_bf16 v[12:15], v[150:153], v[238:241], v[12:15]
	v_mfma_f32_16x16x32_bf16 v[8:11], v[166:169], v[238:241], v[8:11]
	v_mfma_f32_16x16x32_bf16 v[54:57], v[194:197], v[210:213], v[54:57]
	v_mfma_f32_16x16x32_bf16 v[50:53], v[202:205], v[210:213], v[50:53]
	v_mfma_f32_16x16x32_bf16 v[38:41], v[194:197], v[218:221], v[38:41]
	v_mfma_f32_16x16x32_bf16 v[34:37], v[202:205], v[218:221], v[34:37]
	v_mfma_f32_16x16x32_bf16 v[20:23], v[194:197], v[226:229], v[20:23]
	v_mfma_f32_16x16x32_bf16 v[16:19], v[202:205], v[226:229], v[16:19]
	v_mfma_f32_16x16x32_bf16 v[4:7], v[194:197], v[234:237], v[4:7]
	v_mfma_f32_16x16x32_bf16 v[0:3], v[202:205], v[234:237], v[0:3]
	v_mfma_f32_16x16x32_bf16 v[54:57], v[198:201], v[214:217], v[54:57]
	v_mfma_f32_16x16x32_bf16 v[50:53], v[206:209], v[214:217], v[50:53]
	v_mfma_f32_16x16x32_bf16 v[38:41], v[198:201], v[222:225], v[38:41]
	v_mfma_f32_16x16x32_bf16 v[34:37], v[206:209], v[222:225], v[34:37]
	v_mfma_f32_16x16x32_bf16 v[20:23], v[198:201], v[230:233], v[20:23]
	v_mfma_f32_16x16x32_bf16 v[16:19], v[206:209], v[230:233], v[16:19]
	v_mfma_f32_16x16x32_bf16 v[4:7], v[198:201], v[238:241], v[4:7]
	v_mfma_f32_16x16x32_bf16 v[0:3], v[206:209], v[238:241], v[0:3]
	s_barrier
	s_add_u32 s82, s82, 0x100
	s_addc_u32 s83, s83, 0
	s_add_u32 vcc_lo, vcc_lo, 0x100
	s_addc_u32 vcc_hi, vcc_hi, 0
	s_cmp_ge_i32 s22, s94
	s_mov_b32 s84, s22
	s_cbranch_scc0 .LBB0_264
	s_and_b64 vcc, exec, s[78:79]
	s_cbranch_vccz .LBB0_267
	s_barrier

.LBB0_296:
	s_add_i32 vcc_hi, s82, 2
	s_add_u32 s0, s80, 0x80
	s_addc_u32 s1, s81, 0
	s_add_i32 s30, 0, 0x10000
	s_cmp_eq_u32 s85, s82
	s_cselect_b32 s83, s45, s1
	s_cselect_b32 s82, s44, s0
	v_add_u32_e32 v146, s30, v139
	s_cselect_b32 s1, s79, vcc_lo
	s_cselect_b32 s0, s78, s90
	s_add_i32 s86, 0, 0x14000
	ds_read_b128 v[150:153], v146
	ds_read_b128 v[154:157], v146 offset:1024
	ds_read_b128 v[158:161], v146 offset:2048
	ds_read_b128 v[162:165], v146 offset:3072
	v_add_u32_e32 v146, s86, v139
	ds_read_b128 v[166:169], v146
	ds_read_b128 v[194:197], v146 offset:1024
	ds_read_b128 v[198:201], v146 offset:2048
	ds_read_b128 v[202:205], v146 offset:3072
	v_lshl_add_u64 v[146:147], s[80:81], 0, v[130:131]
	s_add_i32 m0, s54, 0xc000
	ds_read_b128 v[206:209], v149
	ds_read_b128 v[210:213], v149 offset:1024
	ds_read_b128 v[214:217], v149 offset:2048
	ds_read_b128 v[218:221], v149 offset:3072
	ds_read_b128 v[222:225], v149 offset:4096
	ds_read_b128 v[226:229], v149 offset:5120
	ds_read_b128 v[230:233], v149 offset:6144
	ds_read_b128 v[234:237], v149 offset:7168
	global_load_lds_dwordx4 v[146:147], off
	v_lshl_add_u64 v[146:147], s[80:81], 0, v[132:133]
	s_add_i32 m0, s54, 0xe000
	s_nop 0
	global_load_lds_dwordx4 v[146:147], off
	s_waitcnt vmcnt(8)
	s_waitcnt lgkmcnt(0)
	s_barrier
	v_mfma_f32_16x16x32_bf16 v[126:129], v[150:153], v[206:209], v[126:129]
	v_mfma_f32_16x16x32_bf16 v[118:121], v[158:161], v[206:209], v[118:121]
	v_mfma_f32_16x16x32_bf16 v[110:113], v[150:153], v[214:217], v[110:113]
	v_mfma_f32_16x16x32_bf16 v[102:105], v[158:161], v[214:217], v[102:105]
	v_mfma_f32_16x16x32_bf16 v[94:97], v[150:153], v[222:225], v[94:97]
	v_mfma_f32_16x16x32_bf16 v[86:89], v[158:161], v[222:225], v[86:89]
	v_mfma_f32_16x16x32_bf16 v[78:81], v[150:153], v[230:233], v[78:81]
	v_mfma_f32_16x16x32_bf16 v[70:73], v[158:161], v[230:233], v[70:73]
	v_mfma_f32_16x16x32_bf16 v[126:129], v[154:157], v[210:213], v[126:129]
	v_mfma_f32_16x16x32_bf16 v[118:121], v[162:165], v[210:213], v[118:121]
	v_mfma_f32_16x16x32_bf16 v[110:113], v[154:157], v[218:221], v[110:113]
	v_mfma_f32_16x16x32_bf16 v[102:105], v[162:165], v[218:221], v[102:105]
	v_mfma_f32_16x16x32_bf16 v[94:97], v[154:157], v[226:229], v[94:97]
	v_mfma_f32_16x16x32_bf16 v[86:89], v[162:165], v[226:229], v[86:89]
	v_mfma_f32_16x16x32_bf16 v[78:81], v[154:157], v[234:237], v[78:81]
	v_mfma_f32_16x16x32_bf16 v[70:73], v[162:165], v[234:237], v[70:73]
	v_mfma_f32_16x16x32_bf16 v[122:125], v[166:169], v[206:209], v[122:125]
	v_mfma_f32_16x16x32_bf16 v[114:117], v[198:201], v[206:209], v[114:117]
	v_mfma_f32_16x16x32_bf16 v[106:109], v[166:169], v[214:217], v[106:109]
	v_mfma_f32_16x16x32_bf16 v[98:101], v[198:201], v[214:217], v[98:101]
	v_mfma_f32_16x16x32_bf16 v[90:93], v[166:169], v[222:225], v[90:93]
	v_mfma_f32_16x16x32_bf16 v[82:85], v[198:201], v[222:225], v[82:85]
	v_mfma_f32_16x16x32_bf16 v[74:77], v[166:169], v[230:233], v[74:77]
	v_mfma_f32_16x16x32_bf16 v[66:69], v[198:201], v[230:233], v[66:69]
	v_mfma_f32_16x16x32_bf16 v[122:125], v[194:197], v[210:213], v[122:125]
	v_mfma_f32_16x16x32_bf16 v[114:117], v[202:205], v[210:213], v[114:117]
	v_mfma_f32_16x16x32_bf16 v[106:109], v[194:197], v[218:221], v[106:109]
	v_mfma_f32_16x16x32_bf16 v[98:101], v[202:205], v[218:221], v[98:101]
	v_mfma_f32_16x16x32_bf16 v[90:93], v[194:197], v[226:229], v[90:93]
	v_mfma_f32_16x16x32_bf16 v[82:85], v[202:205], v[226:229], v[82:85]
	v_mfma_f32_16x16x32_bf16 v[74:77], v[194:197], v[234:237], v[74:77]
	v_mfma_f32_16x16x32_bf16 v[66:69], v[202:205], v[234:237], v[66:69]
	s_barrier
	s_add_i32 s30, s30, s25
	v_lshl_add_u64 v[146:147], s[0:1], 0, v[32:33]
	s_mov_b32 m0, s30
	ds_read_b128 v[206:209], v149 offset:16384
	ds_read_b128 v[210:213], v149 offset:17408
	ds_read_b128 v[214:217], v149 offset:18432
	ds_read_b128 v[218:221], v149 offset:19456
	ds_read_b128 v[222:225], v149 offset:20480
	ds_read_b128 v[226:229], v149 offset:21504
	ds_read_b128 v[230:233], v149 offset:22528
	ds_read_b128 v[234:237], v149 offset:23552
	global_load_lds_dwordx4 v[146:147], off
	s_add_i32 m0, s30, 0x2000
	v_lshl_add_u64 v[238:239], s[0:1], 0, v[144:145]
	s_add_u32 s0, s0, s66
	s_addc_u32 s1, s1, s67
	s_add_i32 s30, s86, s25
	global_load_lds_dwordx4 v[238:239], off
	v_lshl_add_u64 v[240:241], s[0:1], 0, v[32:33]
	s_mov_b32 m0, s30
	v_lshl_add_u64 v[242:243], s[0:1], 0, v[144:145]
	global_load_lds_dwordx4 v[240:241], off
	s_add_i32 m0, s30, 0x2000
	v_lshl_add_u64 v[244:245], s[82:83], 0, v[140:141]
	global_load_lds_dwordx4 v[242:243], off
	s_mov_b32 m0, s54
	v_lshl_add_u64 v[246:247], s[82:83], 0, v[142:143]
	global_load_lds_dwordx4 v[244:245], off
	s_mov_b32 m0, s55
	s_nop 0
	global_load_lds_dwordx4 v[246:247], off
	s_waitcnt vmcnt(8)
	s_waitcnt lgkmcnt(0)
	s_barrier
	v_mfma_f32_16x16x32_bf16 v[62:65], v[150:153], v[206:209], v[62:65]
	v_mfma_f32_16x16x32_bf16 v[54:57], v[158:161], v[206:209], v[54:57]
	v_mfma_f32_16x16x32_bf16 v[46:49], v[150:153], v[214:217], v[46:49]
	v_mfma_f32_16x16x32_bf16 v[38:41], v[158:161], v[214:217], v[38:41]
	v_mfma_f32_16x16x32_bf16 v[28:31], v[150:153], v[222:225], v[28:31]
	v_mfma_f32_16x16x32_bf16 v[20:23], v[158:161], v[222:225], v[20:23]
	v_mfma_f32_16x16x32_bf16 v[12:15], v[150:153], v[230:233], v[12:15]
	v_mfma_f32_16x16x32_bf16 v[4:7], v[158:161], v[230:233], v[4:7]
	v_mfma_f32_16x16x32_bf16 v[62:65], v[154:157], v[210:213], v[62:65]
	v_mfma_f32_16x16x32_bf16 v[54:57], v[162:165], v[210:213], v[54:57]
	v_mfma_f32_16x16x32_bf16 v[46:49], v[154:157], v[218:221], v[46:49]
	v_mfma_f32_16x16x32_bf16 v[38:41], v[162:165], v[218:221], v[38:41]
	v_mfma_f32_16x16x32_bf16 v[28:31], v[154:157], v[226:229], v[28:31]
	v_mfma_f32_16x16x32_bf16 v[20:23], v[162:165], v[226:229], v[20:23]
	v_mfma_f32_16x16x32_bf16 v[12:15], v[154:157], v[234:237], v[12:15]
	v_mfma_f32_16x16x32_bf16 v[4:7], v[162:165], v[234:237], v[4:7]
	v_mfma_f32_16x16x32_bf16 v[58:61], v[166:169], v[206:209], v[58:61]
	v_mfma_f32_16x16x32_bf16 v[50:53], v[198:201], v[206:209], v[50:53]
	v_mfma_f32_16x16x32_bf16 v[42:45], v[166:169], v[214:217], v[42:45]
	v_mfma_f32_16x16x32_bf16 v[34:37], v[198:201], v[214:217], v[34:37]
	v_mfma_f32_16x16x32_bf16 v[24:27], v[166:169], v[222:225], v[24:27]
	v_mfma_f32_16x16x32_bf16 v[16:19], v[198:201], v[222:225], v[16:19]
	v_mfma_f32_16x16x32_bf16 v[8:11], v[166:169], v[230:233], v[8:11]
	v_mfma_f32_16x16x32_bf16 v[0:3], v[198:201], v[230:233], v[0:3]
	v_mfma_f32_16x16x32_bf16 v[58:61], v[194:197], v[210:213], v[58:61]
	v_mfma_f32_16x16x32_bf16 v[50:53], v[202:205], v[210:213], v[50:53]
	v_mfma_f32_16x16x32_bf16 v[42:45], v[194:197], v[218:221], v[42:45]
	v_mfma_f32_16x16x32_bf16 v[34:37], v[202:205], v[218:221], v[34:37]
	v_mfma_f32_16x16x32_bf16 v[24:27], v[194:197], v[226:229], v[24:27]
	v_mfma_f32_16x16x32_bf16 v[16:19], v[202:205], v[226:229], v[16:19]
	v_mfma_f32_16x16x32_bf16 v[8:11], v[194:197], v[234:237], v[8:11]
	v_mfma_f32_16x16x32_bf16 v[0:3], v[202:205], v[234:237], v[0:3]
	s_barrier
	s_add_i32 s30, 0, 0x18000
	s_add_i32 s86, 0, 0x1c000
	v_add_u32_e32 v162, s30, v139
	v_add_u32_e32 v181, s86, v139
	ds_read_b128 v[150:153], v162
	ds_read_b128 v[154:157], v162 offset:1024
	ds_read_b128 v[158:161], v162 offset:2048
	ds_read_b128 v[162:165], v162 offset:3072
	ds_read_b128 v[166:169], v181
	ds_read_b128 v[194:197], v181 offset:1024
	ds_read_b128 v[198:201], v181 offset:2048
	ds_read_b128 v[202:205], v181 offset:3072
	s_add_u32 s0, s82, s66
	s_addc_u32 s1, s83, s67
	s_mov_b32 m0, s56
	v_lshl_add_u64 v[248:249], s[0:1], 0, v[140:141]
	ds_read_b128 v[206:209], v149 offset:32768
	ds_read_b128 v[210:213], v149 offset:33792
	ds_read_b128 v[214:217], v149 offset:34816
	ds_read_b128 v[218:221], v149 offset:35840
	ds_read_b128 v[222:225], v149 offset:36864
	ds_read_b128 v[226:229], v149 offset:37888
	ds_read_b128 v[230:233], v149 offset:38912
	ds_read_b128 v[234:237], v149 offset:39936
	global_load_lds_dwordx4 v[248:249], off
	v_lshl_add_u64 v[248:249], s[0:1], 0, v[142:143]
	s_mov_b32 m0, s57
	s_nop 0
	global_load_lds_dwordx4 v[248:249], off
	s_waitcnt vmcnt(8)
	s_waitcnt lgkmcnt(0)
	s_barrier
	v_mfma_f32_16x16x32_bf16 v[126:129], v[150:153], v[206:209], v[126:129]
	v_mfma_f32_16x16x32_bf16 v[118:121], v[158:161], v[206:209], v[118:121]
	v_mfma_f32_16x16x32_bf16 v[110:113], v[150:153], v[214:217], v[110:113]
	v_mfma_f32_16x16x32_bf16 v[102:105], v[158:161], v[214:217], v[102:105]
	v_mfma_f32_16x16x32_bf16 v[94:97], v[150:153], v[222:225], v[94:97]
	v_mfma_f32_16x16x32_bf16 v[86:89], v[158:161], v[222:225], v[86:89]
	v_mfma_f32_16x16x32_bf16 v[78:81], v[150:153], v[230:233], v[78:81]
	v_mfma_f32_16x16x32_bf16 v[70:73], v[158:161], v[230:233], v[70:73]
	v_mfma_f32_16x16x32_bf16 v[126:129], v[154:157], v[210:213], v[126:129]
	v_mfma_f32_16x16x32_bf16 v[118:121], v[162:165], v[210:213], v[118:121]
	v_mfma_f32_16x16x32_bf16 v[110:113], v[154:157], v[218:221], v[110:113]
	v_mfma_f32_16x16x32_bf16 v[102:105], v[162:165], v[218:221], v[102:105]
	v_mfma_f32_16x16x32_bf16 v[94:97], v[154:157], v[226:229], v[94:97]
	v_mfma_f32_16x16x32_bf16 v[86:89], v[162:165], v[226:229], v[86:89]
	v_mfma_f32_16x16x32_bf16 v[78:81], v[154:157], v[234:237], v[78:81]
	v_mfma_f32_16x16x32_bf16 v[70:73], v[162:165], v[234:237], v[70:73]
	v_mfma_f32_16x16x32_bf16 v[122:125], v[166:169], v[206:209], v[122:125]
	v_mfma_f32_16x16x32_bf16 v[114:117], v[198:201], v[206:209], v[114:117]
	v_mfma_f32_16x16x32_bf16 v[106:109], v[166:169], v[214:217], v[106:109]
	v_mfma_f32_16x16x32_bf16 v[98:101], v[198:201], v[214:217], v[98:101]
	v_mfma_f32_16x16x32_bf16 v[90:93], v[166:169], v[222:225], v[90:93]
	v_mfma_f32_16x16x32_bf16 v[82:85], v[198:201], v[222:225], v[82:85]
	v_mfma_f32_16x16x32_bf16 v[74:77], v[166:169], v[230:233], v[74:77]
	v_mfma_f32_16x16x32_bf16 v[66:69], v[198:201], v[230:233], v[66:69]
	v_mfma_f32_16x16x32_bf16 v[122:125], v[194:197], v[210:213], v[122:125]
	v_mfma_f32_16x16x32_bf16 v[114:117], v[202:205], v[210:213], v[114:117]
	v_mfma_f32_16x16x32_bf16 v[106:109], v[194:197], v[218:221], v[106:109]
	v_mfma_f32_16x16x32_bf16 v[98:101], v[202:205], v[218:221], v[98:101]
	v_mfma_f32_16x16x32_bf16 v[90:93], v[194:197], v[226:229], v[90:93]
	v_mfma_f32_16x16x32_bf16 v[82:85], v[202:205], v[226:229], v[82:85]
	v_mfma_f32_16x16x32_bf16 v[74:77], v[194:197], v[234:237], v[74:77]
	v_mfma_f32_16x16x32_bf16 v[66:69], v[202:205], v[234:237], v[66:69]
	s_barrier
	s_add_i32 s0, s30, s25
	v_lshl_add_u64 v[146:147], v[146:147], 0, s[26:27]
	s_mov_b32 m0, s0
	ds_read_b128 v[206:209], v149 offset:49152
	ds_read_b128 v[210:213], v149 offset:50176
	ds_read_b128 v[214:217], v149 offset:51200
	ds_read_b128 v[218:221], v149 offset:52224
	ds_read_b128 v[222:225], v149 offset:53248
	ds_read_b128 v[226:229], v149 offset:54272
	ds_read_b128 v[230:233], v149 offset:55296
	ds_read_b128 v[234:237], v149 offset:56320
	global_load_lds_dwordx4 v[146:147], off
	v_lshl_add_u64 v[146:147], v[238:239], 0, s[26:27]
	s_add_i32 m0, s0, 0x2000
	s_add_i32 s0, s86, s25
	global_load_lds_dwordx4 v[146:147], off
	v_lshl_add_u64 v[146:147], v[240:241], 0, s[26:27]
	s_mov_b32 m0, s0
	s_nop 0
	global_load_lds_dwordx4 v[146:147], off
	v_lshl_add_u64 v[146:147], v[242:243], 0, s[26:27]
	s_add_i32 m0, s0, 0x2000
	s_nop 0
	global_load_lds_dwordx4 v[146:147], off
	v_lshl_add_u64 v[146:147], v[244:245], 0, s[26:27]
	s_mov_b32 m0, s71
	s_nop 0
	global_load_lds_dwordx4 v[146:147], off
	v_lshl_add_u64 v[146:147], v[246:247], 0, s[26:27]
	s_mov_b32 m0, s84
	s_nop 0
	global_load_lds_dwordx4 v[146:147], off
	s_waitcnt vmcnt(8)
	s_waitcnt lgkmcnt(0)
	s_barrier
	v_mfma_f32_16x16x32_bf16 v[62:65], v[150:153], v[206:209], v[62:65]
	v_mfma_f32_16x16x32_bf16 v[54:57], v[158:161], v[206:209], v[54:57]
	v_mfma_f32_16x16x32_bf16 v[46:49], v[150:153], v[214:217], v[46:49]
	v_mfma_f32_16x16x32_bf16 v[38:41], v[158:161], v[214:217], v[38:41]
	v_mfma_f32_16x16x32_bf16 v[28:31], v[150:153], v[222:225], v[28:31]
	v_mfma_f32_16x16x32_bf16 v[20:23], v[158:161], v[222:225], v[20:23]
	v_mfma_f32_16x16x32_bf16 v[12:15], v[150:153], v[230:233], v[12:15]
	v_mfma_f32_16x16x32_bf16 v[4:7], v[158:161], v[230:233], v[4:7]
	v_mfma_f32_16x16x32_bf16 v[62:65], v[154:157], v[210:213], v[62:65]
	v_mfma_f32_16x16x32_bf16 v[54:57], v[162:165], v[210:213], v[54:57]
	v_mfma_f32_16x16x32_bf16 v[46:49], v[154:157], v[218:221], v[46:49]
	v_mfma_f32_16x16x32_bf16 v[38:41], v[162:165], v[218:221], v[38:41]
	v_mfma_f32_16x16x32_bf16 v[28:31], v[154:157], v[226:229], v[28:31]
	v_mfma_f32_16x16x32_bf16 v[20:23], v[162:165], v[226:229], v[20:23]
	v_mfma_f32_16x16x32_bf16 v[12:15], v[154:157], v[234:237], v[12:15]
	v_mfma_f32_16x16x32_bf16 v[4:7], v[162:165], v[234:237], v[4:7]
	v_mfma_f32_16x16x32_bf16 v[58:61], v[166:169], v[206:209], v[58:61]
	v_mfma_f32_16x16x32_bf16 v[50:53], v[198:201], v[206:209], v[50:53]
	v_mfma_f32_16x16x32_bf16 v[42:45], v[166:169], v[214:217], v[42:45]
	v_mfma_f32_16x16x32_bf16 v[34:37], v[198:201], v[214:217], v[34:37]
	v_mfma_f32_16x16x32_bf16 v[24:27], v[166:169], v[222:225], v[24:27]
	v_mfma_f32_16x16x32_bf16 v[16:19], v[198:201], v[222:225], v[16:19]
	v_mfma_f32_16x16x32_bf16 v[8:11], v[166:169], v[230:233], v[8:11]
	v_mfma_f32_16x16x32_bf16 v[0:3], v[198:201], v[230:233], v[0:3]
	v_mfma_f32_16x16x32_bf16 v[58:61], v[194:197], v[210:213], v[58:61]
	v_mfma_f32_16x16x32_bf16 v[50:53], v[202:205], v[210:213], v[50:53]
	v_mfma_f32_16x16x32_bf16 v[42:45], v[194:197], v[218:221], v[42:45]
	v_mfma_f32_16x16x32_bf16 v[34:37], v[202:205], v[218:221], v[34:37]
	v_mfma_f32_16x16x32_bf16 v[24:27], v[194:197], v[226:229], v[24:27]
	v_mfma_f32_16x16x32_bf16 v[16:19], v[202:205], v[226:229], v[16:19]
	v_mfma_f32_16x16x32_bf16 v[8:11], v[194:197], v[234:237], v[8:11]
	v_mfma_f32_16x16x32_bf16 v[0:3], v[202:205], v[234:237], v[0:3]
	s_barrier
	s_add_u32 s80, s80, 0x100
	s_addc_u32 s81, s81, 0
	s_add_u32 s90, s90, 0x100
	s_addc_u32 vcc_lo, vcc_lo, 0
	s_cmp_ge_i32 vcc_hi, s94
	s_mov_b32 s82, vcc_hi
	s_cbranch_scc0 .LBB0_296
	s_and_b64 vcc, exec, s[76:77]
	s_cbranch_vccz .LBB0_299
	s_barrier

.LBB0_327:
	s_add_i32 s0, s80, 2
	s_add_u32 s1, s78, 0x80
	s_addc_u32 s30, s79, 0
	s_add_i32 s86, 0, 0x10000
	s_cmp_eq_u32 s82, s80
	s_cselect_b32 s81, s45, s30
	s_cselect_b32 s80, s44, s1
	s_cselect_b32 s99, s77, s97
	s_cselect_b32 s98, s76, s96
	s_add_i32 s1, 0, 0x14000
	v_add_u32_e32 v160, s86, v139
	v_add_u32_e32 v168, s1, v139
	ds_read_b128 v[146:149], v160
	ds_read_b128 v[152:155], v160 offset:1024
	ds_read_b128 v[156:159], v160 offset:2048
	ds_read_b128 v[160:163], v160 offset:3072
	ds_read_b128 v[164:167], v168
	ds_read_b128 v[194:197], v168 offset:1024
	ds_read_b128 v[198:201], v168 offset:2048
	ds_read_b128 v[202:205], v168 offset:3072
	v_lshl_add_u64 v[168:169], s[78:79], 0, v[130:131]
	s_add_i32 m0, s53, 0xc000
	ds_read_b128 v[206:209], v151
	ds_read_b128 v[210:213], v151 offset:1024
	ds_read_b128 v[214:217], v151 offset:2048
	ds_read_b128 v[218:221], v151 offset:3072
	ds_read_b128 v[222:225], v151 offset:4096
	ds_read_b128 v[226:229], v151 offset:5120
	ds_read_b128 v[230:233], v151 offset:6144
	ds_read_b128 v[234:237], v151 offset:7168
	global_load_lds_dwordx4 v[168:169], off
	v_lshl_add_u64 v[168:169], s[78:79], 0, v[132:133]
	s_add_i32 m0, s53, 0xe000
	s_nop 0
	global_load_lds_dwordx4 v[168:169], off
	s_waitcnt vmcnt(8)
	s_waitcnt lgkmcnt(0)
	s_barrier
	v_mfma_f32_16x16x32_bf16 v[126:129], v[146:149], v[206:209], v[126:129]
	v_mfma_f32_16x16x32_bf16 v[122:125], v[156:159], v[206:209], v[122:125]
	v_mfma_f32_16x16x32_bf16 v[110:113], v[146:149], v[214:217], v[110:113]
	v_mfma_f32_16x16x32_bf16 v[106:109], v[156:159], v[214:217], v[106:109]
	v_mfma_f32_16x16x32_bf16 v[94:97], v[146:149], v[222:225], v[94:97]
	v_mfma_f32_16x16x32_bf16 v[90:93], v[156:159], v[222:225], v[90:93]
	v_mfma_f32_16x16x32_bf16 v[78:81], v[146:149], v[230:233], v[78:81]
	v_mfma_f32_16x16x32_bf16 v[74:77], v[156:159], v[230:233], v[74:77]
	v_mfma_f32_16x16x32_bf16 v[126:129], v[152:155], v[210:213], v[126:129]
	v_mfma_f32_16x16x32_bf16 v[122:125], v[160:163], v[210:213], v[122:125]
	v_mfma_f32_16x16x32_bf16 v[110:113], v[152:155], v[218:221], v[110:113]
	v_mfma_f32_16x16x32_bf16 v[106:109], v[160:163], v[218:221], v[106:109]
	v_mfma_f32_16x16x32_bf16 v[94:97], v[152:155], v[226:229], v[94:97]
	v_mfma_f32_16x16x32_bf16 v[90:93], v[160:163], v[226:229], v[90:93]
	v_mfma_f32_16x16x32_bf16 v[78:81], v[152:155], v[234:237], v[78:81]
	v_mfma_f32_16x16x32_bf16 v[74:77], v[160:163], v[234:237], v[74:77]
	v_mfma_f32_16x16x32_bf16 v[118:121], v[164:167], v[206:209], v[118:121]
	v_mfma_f32_16x16x32_bf16 v[114:117], v[198:201], v[206:209], v[114:117]
	v_mfma_f32_16x16x32_bf16 v[102:105], v[164:167], v[214:217], v[102:105]
	v_mfma_f32_16x16x32_bf16 v[98:101], v[198:201], v[214:217], v[98:101]
	v_mfma_f32_16x16x32_bf16 v[86:89], v[164:167], v[222:225], v[86:89]
	v_mfma_f32_16x16x32_bf16 v[82:85], v[198:201], v[222:225], v[82:85]
	v_mfma_f32_16x16x32_bf16 v[70:73], v[164:167], v[230:233], v[70:73]
	v_mfma_f32_16x16x32_bf16 v[66:69], v[198:201], v[230:233], v[66:69]
	v_mfma_f32_16x16x32_bf16 v[118:121], v[194:197], v[210:213], v[118:121]
	v_mfma_f32_16x16x32_bf16 v[114:117], v[202:205], v[210:213], v[114:117]
	v_mfma_f32_16x16x32_bf16 v[102:105], v[194:197], v[218:221], v[102:105]
	v_mfma_f32_16x16x32_bf16 v[98:101], v[202:205], v[218:221], v[98:101]
	v_mfma_f32_16x16x32_bf16 v[86:89], v[194:197], v[226:229], v[86:89]
	v_mfma_f32_16x16x32_bf16 v[82:85], v[202:205], v[226:229], v[82:85]
	v_mfma_f32_16x16x32_bf16 v[70:73], v[194:197], v[234:237], v[70:73]
	v_mfma_f32_16x16x32_bf16 v[66:69], v[202:205], v[234:237], v[66:69]
	s_barrier
	s_add_i32 s30, s86, s23
	v_lshl_add_u64 v[168:169], s[98:99], 0, v[32:33]
	s_mov_b32 m0, s30
	ds_read_b128 v[206:209], v151 offset:16384
	ds_read_b128 v[210:213], v151 offset:17408
	ds_read_b128 v[214:217], v151 offset:18432
	ds_read_b128 v[218:221], v151 offset:19456
	ds_read_b128 v[222:225], v151 offset:20480
	ds_read_b128 v[226:229], v151 offset:21504
	ds_read_b128 v[230:233], v151 offset:22528
	ds_read_b128 v[234:237], v151 offset:23552
	global_load_lds_dwordx4 v[168:169], off
	s_add_i32 m0, s30, 0x2000
	v_lshl_add_u64 v[238:239], s[98:99], 0, v[144:145]
	s_add_u32 s98, s98, s66
	s_addc_u32 s99, s99, s67
	s_add_i32 s1, s1, s23
	global_load_lds_dwordx4 v[238:239], off
	v_lshl_add_u64 v[240:241], s[98:99], 0, v[32:33]
	s_mov_b32 m0, s1
	v_lshl_add_u64 v[242:243], s[98:99], 0, v[144:145]
	global_load_lds_dwordx4 v[240:241], off
	s_add_i32 m0, s1, 0x2000
	v_lshl_add_u64 v[244:245], s[80:81], 0, v[140:141]
	global_load_lds_dwordx4 v[242:243], off
	s_mov_b32 m0, s53
	v_lshl_add_u64 v[246:247], s[80:81], 0, v[142:143]
	global_load_lds_dwordx4 v[244:245], off
	s_mov_b32 m0, s54
	s_nop 0
	global_load_lds_dwordx4 v[246:247], off
	s_waitcnt vmcnt(8)
	s_waitcnt lgkmcnt(0)
	s_barrier
	v_mfma_f32_16x16x32_bf16 v[62:65], v[146:149], v[206:209], v[62:65]
	v_mfma_f32_16x16x32_bf16 v[58:61], v[156:159], v[206:209], v[58:61]
	v_mfma_f32_16x16x32_bf16 v[46:49], v[146:149], v[214:217], v[46:49]
	v_mfma_f32_16x16x32_bf16 v[42:45], v[156:159], v[214:217], v[42:45]
	v_mfma_f32_16x16x32_bf16 v[28:31], v[146:149], v[222:225], v[28:31]
	v_mfma_f32_16x16x32_bf16 v[24:27], v[156:159], v[222:225], v[24:27]
	v_mfma_f32_16x16x32_bf16 v[12:15], v[146:149], v[230:233], v[12:15]
	v_mfma_f32_16x16x32_bf16 v[8:11], v[156:159], v[230:233], v[8:11]
	v_mfma_f32_16x16x32_bf16 v[62:65], v[152:155], v[210:213], v[62:65]
	v_mfma_f32_16x16x32_bf16 v[58:61], v[160:163], v[210:213], v[58:61]
	v_mfma_f32_16x16x32_bf16 v[46:49], v[152:155], v[218:221], v[46:49]
	v_mfma_f32_16x16x32_bf16 v[42:45], v[160:163], v[218:221], v[42:45]
	v_mfma_f32_16x16x32_bf16 v[28:31], v[152:155], v[226:229], v[28:31]
	v_mfma_f32_16x16x32_bf16 v[24:27], v[160:163], v[226:229], v[24:27]
	v_mfma_f32_16x16x32_bf16 v[12:15], v[152:155], v[234:237], v[12:15]
	v_mfma_f32_16x16x32_bf16 v[8:11], v[160:163], v[234:237], v[8:11]
	v_mfma_f32_16x16x32_bf16 v[54:57], v[164:167], v[206:209], v[54:57]
	v_mfma_f32_16x16x32_bf16 v[50:53], v[198:201], v[206:209], v[50:53]
	v_mfma_f32_16x16x32_bf16 v[38:41], v[164:167], v[214:217], v[38:41]
	v_mfma_f32_16x16x32_bf16 v[34:37], v[198:201], v[214:217], v[34:37]
	v_mfma_f32_16x16x32_bf16 v[20:23], v[164:167], v[222:225], v[20:23]
	v_mfma_f32_16x16x32_bf16 v[16:19], v[198:201], v[222:225], v[16:19]
	v_mfma_f32_16x16x32_bf16 v[4:7], v[164:167], v[230:233], v[4:7]
	v_mfma_f32_16x16x32_bf16 v[0:3], v[198:201], v[230:233], v[0:3]
	v_mfma_f32_16x16x32_bf16 v[54:57], v[194:197], v[210:213], v[54:57]
	v_mfma_f32_16x16x32_bf16 v[50:53], v[202:205], v[210:213], v[50:53]
	v_mfma_f32_16x16x32_bf16 v[38:41], v[194:197], v[218:221], v[38:41]
	v_mfma_f32_16x16x32_bf16 v[34:37], v[202:205], v[218:221], v[34:37]
	v_mfma_f32_16x16x32_bf16 v[20:23], v[194:197], v[226:229], v[20:23]
	v_mfma_f32_16x16x32_bf16 v[16:19], v[202:205], v[226:229], v[16:19]
	v_mfma_f32_16x16x32_bf16 v[4:7], v[194:197], v[234:237], v[4:7]
	v_mfma_f32_16x16x32_bf16 v[0:3], v[202:205], v[234:237], v[0:3]
	s_barrier
	s_add_i32 s1, 0, 0x18000
	s_add_i32 s30, 0, 0x1c000
	v_add_u32_e32 v160, s1, v139
	v_add_u32_e32 v181, s30, v139
	ds_read_b128 v[146:149], v160
	ds_read_b128 v[152:155], v160 offset:1024
	ds_read_b128 v[156:159], v160 offset:2048
	ds_read_b128 v[160:163], v160 offset:3072
	ds_read_b128 v[164:167], v181
	ds_read_b128 v[194:197], v181 offset:1024
	ds_read_b128 v[198:201], v181 offset:2048
	ds_read_b128 v[202:205], v181 offset:3072
	s_add_u32 s80, s80, s66
	s_addc_u32 s81, s81, s67
	s_mov_b32 m0, s55
	v_lshl_add_u64 v[248:249], s[80:81], 0, v[140:141]
	ds_read_b128 v[206:209], v151 offset:32768
	ds_read_b128 v[210:213], v151 offset:33792
	ds_read_b128 v[214:217], v151 offset:34816
	ds_read_b128 v[218:221], v151 offset:35840
	ds_read_b128 v[222:225], v151 offset:36864
	ds_read_b128 v[226:229], v151 offset:37888
	ds_read_b128 v[230:233], v151 offset:38912
	ds_read_b128 v[234:237], v151 offset:39936
	global_load_lds_dwordx4 v[248:249], off
	v_lshl_add_u64 v[248:249], s[80:81], 0, v[142:143]
	s_mov_b32 m0, s56
	s_nop 0
	global_load_lds_dwordx4 v[248:249], off
	s_waitcnt vmcnt(8)
	s_waitcnt lgkmcnt(0)
	s_barrier
	v_mfma_f32_16x16x32_bf16 v[126:129], v[146:149], v[206:209], v[126:129]
	v_mfma_f32_16x16x32_bf16 v[122:125], v[156:159], v[206:209], v[122:125]
	v_mfma_f32_16x16x32_bf16 v[110:113], v[146:149], v[214:217], v[110:113]
	v_mfma_f32_16x16x32_bf16 v[106:109], v[156:159], v[214:217], v[106:109]
	v_mfma_f32_16x16x32_bf16 v[94:97], v[146:149], v[222:225], v[94:97]
	v_mfma_f32_16x16x32_bf16 v[90:93], v[156:159], v[222:225], v[90:93]
	v_mfma_f32_16x16x32_bf16 v[78:81], v[146:149], v[230:233], v[78:81]
	v_mfma_f32_16x16x32_bf16 v[74:77], v[156:159], v[230:233], v[74:77]
	v_mfma_f32_16x16x32_bf16 v[126:129], v[152:155], v[210:213], v[126:129]
	v_mfma_f32_16x16x32_bf16 v[122:125], v[160:163], v[210:213], v[122:125]
	v_mfma_f32_16x16x32_bf16 v[110:113], v[152:155], v[218:221], v[110:113]
	v_mfma_f32_16x16x32_bf16 v[106:109], v[160:163], v[218:221], v[106:109]
	v_mfma_f32_16x16x32_bf16 v[94:97], v[152:155], v[226:229], v[94:97]
	v_mfma_f32_16x16x32_bf16 v[90:93], v[160:163], v[226:229], v[90:93]
	v_mfma_f32_16x16x32_bf16 v[78:81], v[152:155], v[234:237], v[78:81]
	v_mfma_f32_16x16x32_bf16 v[74:77], v[160:163], v[234:237], v[74:77]
	v_mfma_f32_16x16x32_bf16 v[118:121], v[164:167], v[206:209], v[118:121]
	v_mfma_f32_16x16x32_bf16 v[114:117], v[198:201], v[206:209], v[114:117]
	v_mfma_f32_16x16x32_bf16 v[102:105], v[164:167], v[214:217], v[102:105]
	v_mfma_f32_16x16x32_bf16 v[98:101], v[198:201], v[214:217], v[98:101]
	v_mfma_f32_16x16x32_bf16 v[86:89], v[164:167], v[222:225], v[86:89]
	v_mfma_f32_16x16x32_bf16 v[82:85], v[198:201], v[222:225], v[82:85]
	v_mfma_f32_16x16x32_bf16 v[70:73], v[164:167], v[230:233], v[70:73]
	v_mfma_f32_16x16x32_bf16 v[66:69], v[198:201], v[230:233], v[66:69]
	v_mfma_f32_16x16x32_bf16 v[118:121], v[194:197], v[210:213], v[118:121]
	v_mfma_f32_16x16x32_bf16 v[114:117], v[202:205], v[210:213], v[114:117]
	v_mfma_f32_16x16x32_bf16 v[102:105], v[194:197], v[218:221], v[102:105]
	v_mfma_f32_16x16x32_bf16 v[98:101], v[202:205], v[218:221], v[98:101]
	v_mfma_f32_16x16x32_bf16 v[86:89], v[194:197], v[226:229], v[86:89]
	v_mfma_f32_16x16x32_bf16 v[82:85], v[202:205], v[226:229], v[82:85]
	v_mfma_f32_16x16x32_bf16 v[70:73], v[194:197], v[234:237], v[70:73]
	v_mfma_f32_16x16x32_bf16 v[66:69], v[202:205], v[234:237], v[66:69]
	s_barrier
	s_add_i32 s1, s1, s23
	v_lshl_add_u64 v[168:169], v[168:169], 0, s[26:27]
	s_mov_b32 m0, s1
	ds_read_b128 v[206:209], v151 offset:49152
	ds_read_b128 v[210:213], v151 offset:50176
	ds_read_b128 v[214:217], v151 offset:51200
	ds_read_b128 v[218:221], v151 offset:52224
	ds_read_b128 v[222:225], v151 offset:53248
	ds_read_b128 v[226:229], v151 offset:54272
	ds_read_b128 v[230:233], v151 offset:55296
	ds_read_b128 v[234:237], v151 offset:56320
	global_load_lds_dwordx4 v[168:169], off
	v_lshl_add_u64 v[168:169], v[238:239], 0, s[26:27]
	s_add_i32 m0, s1, 0x2000
	s_add_i32 s1, s30, s23
	global_load_lds_dwordx4 v[168:169], off
	v_lshl_add_u64 v[168:169], v[240:241], 0, s[26:27]
	s_mov_b32 m0, s1
	s_nop 0
	global_load_lds_dwordx4 v[168:169], off
	v_lshl_add_u64 v[168:169], v[242:243], 0, s[26:27]
	s_add_i32 m0, s1, 0x2000
	s_nop 0
	global_load_lds_dwordx4 v[168:169], off
	v_lshl_add_u64 v[168:169], v[244:245], 0, s[26:27]
	s_mov_b32 m0, s57
	s_nop 0
	global_load_lds_dwordx4 v[168:169], off
	v_lshl_add_u64 v[168:169], v[246:247], 0, s[26:27]
	s_mov_b32 m0, s71
	s_nop 0
	global_load_lds_dwordx4 v[168:169], off
	s_waitcnt vmcnt(8)
	s_waitcnt lgkmcnt(0)
	s_barrier
	v_mfma_f32_16x16x32_bf16 v[62:65], v[146:149], v[206:209], v[62:65]
	v_mfma_f32_16x16x32_bf16 v[58:61], v[156:159], v[206:209], v[58:61]
	v_mfma_f32_16x16x32_bf16 v[46:49], v[146:149], v[214:217], v[46:49]
	v_mfma_f32_16x16x32_bf16 v[42:45], v[156:159], v[214:217], v[42:45]
	v_mfma_f32_16x16x32_bf16 v[28:31], v[146:149], v[222:225], v[28:31]
	v_mfma_f32_16x16x32_bf16 v[24:27], v[156:159], v[222:225], v[24:27]
	v_mfma_f32_16x16x32_bf16 v[12:15], v[146:149], v[230:233], v[12:15]
	v_mfma_f32_16x16x32_bf16 v[8:11], v[156:159], v[230:233], v[8:11]
	v_mfma_f32_16x16x32_bf16 v[62:65], v[152:155], v[210:213], v[62:65]
	v_mfma_f32_16x16x32_bf16 v[58:61], v[160:163], v[210:213], v[58:61]
	v_mfma_f32_16x16x32_bf16 v[46:49], v[152:155], v[218:221], v[46:49]
	v_mfma_f32_16x16x32_bf16 v[42:45], v[160:163], v[218:221], v[42:45]
	v_mfma_f32_16x16x32_bf16 v[28:31], v[152:155], v[226:229], v[28:31]
	v_mfma_f32_16x16x32_bf16 v[24:27], v[160:163], v[226:229], v[24:27]
	v_mfma_f32_16x16x32_bf16 v[12:15], v[152:155], v[234:237], v[12:15]
	v_mfma_f32_16x16x32_bf16 v[8:11], v[160:163], v[234:237], v[8:11]
	v_mfma_f32_16x16x32_bf16 v[54:57], v[164:167], v[206:209], v[54:57]
	v_mfma_f32_16x16x32_bf16 v[50:53], v[198:201], v[206:209], v[50:53]
	v_mfma_f32_16x16x32_bf16 v[38:41], v[164:167], v[214:217], v[38:41]
	v_mfma_f32_16x16x32_bf16 v[34:37], v[198:201], v[214:217], v[34:37]
	v_mfma_f32_16x16x32_bf16 v[20:23], v[164:167], v[222:225], v[20:23]
	v_mfma_f32_16x16x32_bf16 v[16:19], v[198:201], v[222:225], v[16:19]
	v_mfma_f32_16x16x32_bf16 v[4:7], v[164:167], v[230:233], v[4:7]
	v_mfma_f32_16x16x32_bf16 v[0:3], v[198:201], v[230:233], v[0:3]
	v_mfma_f32_16x16x32_bf16 v[54:57], v[194:197], v[210:213], v[54:57]
	v_mfma_f32_16x16x32_bf16 v[50:53], v[202:205], v[210:213], v[50:53]
	v_mfma_f32_16x16x32_bf16 v[38:41], v[194:197], v[218:221], v[38:41]
	v_mfma_f32_16x16x32_bf16 v[34:37], v[202:205], v[218:221], v[34:37]
	v_mfma_f32_16x16x32_bf16 v[20:23], v[194:197], v[226:229], v[20:23]
	v_mfma_f32_16x16x32_bf16 v[16:19], v[202:205], v[226:229], v[16:19]
	v_mfma_f32_16x16x32_bf16 v[4:7], v[194:197], v[234:237], v[4:7]
	v_mfma_f32_16x16x32_bf16 v[0:3], v[202:205], v[234:237], v[0:3]
	s_barrier
	s_add_u32 s78, s78, 0x100
	s_addc_u32 s79, s79, 0
	s_add_u32 s96, s96, 0x100
	s_addc_u32 s97, s97, 0
	s_cmp_ge_i32 s0, s94
	s_mov_b32 s80, s0
	s_cbranch_scc0 .LBB0_327
	s_and_b64 vcc, exec, s[74:75]
	s_cbranch_vccz .LBB0_330
	s_barrier

.LBB0_356:
	s_add_i32 s91, s76, 2
	s_add_u32 s0, s74, 0x80
	s_addc_u32 s1, s75, 0
	s_add_i32 s95, 0, 0x10000
	s_cmp_eq_u32 s81, s76
	s_cselect_b32 s77, s43, s1
	s_cselect_b32 s76, s42, s0
	s_cselect_b32 s1, s71, s90
	s_cselect_b32 s0, s70, s85
	s_add_i32 s96, 0, 0x14000
	v_add_u32_e32 v160, s95, v139
	v_add_u32_e32 v168, s96, v139
	ds_read_b128 v[148:151], v160
	ds_read_b128 v[152:155], v160 offset:1024
	ds_read_b128 v[156:159], v160 offset:2048
	ds_read_b128 v[160:163], v160 offset:3072
	ds_read_b128 v[164:167], v168
	ds_read_b128 v[194:197], v168 offset:1024
	ds_read_b128 v[198:201], v168 offset:2048
	ds_read_b128 v[202:205], v168 offset:3072
	v_lshl_add_u64 v[168:169], s[74:75], 0, v[130:131]
	s_add_i32 m0, s53, 0xc000
	ds_read_b128 v[206:209], v147
	ds_read_b128 v[210:213], v147 offset:1024
	ds_read_b128 v[214:217], v147 offset:2048
	ds_read_b128 v[218:221], v147 offset:3072
	ds_read_b128 v[222:225], v147 offset:4096
	ds_read_b128 v[226:229], v147 offset:5120
	ds_read_b128 v[230:233], v147 offset:6144
	ds_read_b128 v[234:237], v147 offset:7168
	global_load_lds_dwordx4 v[168:169], off
	v_lshl_add_u64 v[168:169], s[74:75], 0, v[132:133]
	s_add_i32 m0, s53, 0xe000
	s_nop 0
	global_load_lds_dwordx4 v[168:169], off
	s_waitcnt vmcnt(8)
	s_waitcnt lgkmcnt(0)
	s_barrier
	v_mfma_f32_16x16x32_bf16 v[126:129], v[148:151], v[206:209], v[126:129]
	v_mfma_f32_16x16x32_bf16 v[122:125], v[156:159], v[206:209], v[122:125]
	v_mfma_f32_16x16x32_bf16 v[118:121], v[148:151], v[214:217], v[118:121]
	v_mfma_f32_16x16x32_bf16 v[114:117], v[156:159], v[214:217], v[114:117]
	v_mfma_f32_16x16x32_bf16 v[102:105], v[148:151], v[222:225], v[102:105]
	v_mfma_f32_16x16x32_bf16 v[98:101], v[156:159], v[222:225], v[98:101]
	v_mfma_f32_16x16x32_bf16 v[86:89], v[148:151], v[230:233], v[86:89]
	v_mfma_f32_16x16x32_bf16 v[82:85], v[156:159], v[230:233], v[82:85]
	v_mfma_f32_16x16x32_bf16 v[126:129], v[152:155], v[210:213], v[126:129]
	v_mfma_f32_16x16x32_bf16 v[122:125], v[160:163], v[210:213], v[122:125]
	v_mfma_f32_16x16x32_bf16 v[118:121], v[152:155], v[218:221], v[118:121]
	v_mfma_f32_16x16x32_bf16 v[114:117], v[160:163], v[218:221], v[114:117]
	v_mfma_f32_16x16x32_bf16 v[102:105], v[152:155], v[226:229], v[102:105]
	v_mfma_f32_16x16x32_bf16 v[98:101], v[160:163], v[226:229], v[98:101]
	v_mfma_f32_16x16x32_bf16 v[86:89], v[152:155], v[234:237], v[86:89]
	v_mfma_f32_16x16x32_bf16 v[82:85], v[160:163], v[234:237], v[82:85]
	v_mfma_f32_16x16x32_bf16 v[110:113], v[164:167], v[206:209], v[110:113]
	v_mfma_f32_16x16x32_bf16 v[106:109], v[198:201], v[206:209], v[106:109]
	v_mfma_f32_16x16x32_bf16 v[94:97], v[164:167], v[214:217], v[94:97]
	v_mfma_f32_16x16x32_bf16 v[90:93], v[198:201], v[214:217], v[90:93]
	v_mfma_f32_16x16x32_bf16 v[78:81], v[164:167], v[222:225], v[78:81]
	v_mfma_f32_16x16x32_bf16 v[74:77], v[198:201], v[222:225], v[74:77]
	v_mfma_f32_16x16x32_bf16 v[70:73], v[164:167], v[230:233], v[70:73]
	v_mfma_f32_16x16x32_bf16 v[66:69], v[198:201], v[230:233], v[66:69]
	v_mfma_f32_16x16x32_bf16 v[110:113], v[194:197], v[210:213], v[110:113]
	v_mfma_f32_16x16x32_bf16 v[106:109], v[202:205], v[210:213], v[106:109]
	v_mfma_f32_16x16x32_bf16 v[94:97], v[194:197], v[218:221], v[94:97]
	v_mfma_f32_16x16x32_bf16 v[90:93], v[202:205], v[218:221], v[90:93]
	v_mfma_f32_16x16x32_bf16 v[78:81], v[194:197], v[226:229], v[78:81]
	v_mfma_f32_16x16x32_bf16 v[74:77], v[202:205], v[226:229], v[74:77]
	v_mfma_f32_16x16x32_bf16 v[70:73], v[194:197], v[234:237], v[70:73]
	v_mfma_f32_16x16x32_bf16 v[66:69], v[202:205], v[234:237], v[66:69]
	s_barrier
	s_add_i32 s95, s95, s23
	v_lshl_add_u64 v[168:169], s[0:1], 0, v[32:33]
	s_mov_b32 m0, s95
	ds_read_b128 v[206:209], v147 offset:16384
	ds_read_b128 v[210:213], v147 offset:17408
	ds_read_b128 v[214:217], v147 offset:18432
	ds_read_b128 v[218:221], v147 offset:19456
	ds_read_b128 v[222:225], v147 offset:20480
	ds_read_b128 v[226:229], v147 offset:21504
	ds_read_b128 v[230:233], v147 offset:22528
	ds_read_b128 v[234:237], v147 offset:23552
	global_load_lds_dwordx4 v[168:169], off
	s_add_i32 m0, s95, 0x2000
	v_lshl_add_u64 v[238:239], s[0:1], 0, v[144:145]
	s_add_u32 s0, s0, s66
	s_addc_u32 s1, s1, s67
	s_add_i32 s95, s96, s23
	global_load_lds_dwordx4 v[238:239], off
	v_lshl_add_u64 v[240:241], s[0:1], 0, v[32:33]
	s_mov_b32 m0, s95
	v_lshl_add_u64 v[242:243], s[0:1], 0, v[144:145]
	global_load_lds_dwordx4 v[240:241], off
	s_add_i32 m0, s95, 0x2000
	v_lshl_add_u64 v[244:245], s[76:77], 0, v[140:141]
	global_load_lds_dwordx4 v[242:243], off
	s_mov_b32 m0, s53
	v_lshl_add_u64 v[246:247], s[76:77], 0, v[142:143]
	global_load_lds_dwordx4 v[244:245], off
	s_mov_b32 m0, s54
	s_nop 0
	global_load_lds_dwordx4 v[246:247], off
	s_waitcnt vmcnt(8)
	s_waitcnt lgkmcnt(0)
	s_barrier
	v_mfma_f32_16x16x32_bf16 v[62:65], v[148:151], v[206:209], v[62:65]
	v_mfma_f32_16x16x32_bf16 v[58:61], v[156:159], v[206:209], v[58:61]
	v_mfma_f32_16x16x32_bf16 v[54:57], v[148:151], v[214:217], v[54:57]
	v_mfma_f32_16x16x32_bf16 v[50:53], v[156:159], v[214:217], v[50:53]
	v_mfma_f32_16x16x32_bf16 v[38:41], v[148:151], v[222:225], v[38:41]
	v_mfma_f32_16x16x32_bf16 v[34:37], v[156:159], v[222:225], v[34:37]
	v_mfma_f32_16x16x32_bf16 v[20:23], v[148:151], v[230:233], v[20:23]
	v_mfma_f32_16x16x32_bf16 v[16:19], v[156:159], v[230:233], v[16:19]
	v_mfma_f32_16x16x32_bf16 v[62:65], v[152:155], v[210:213], v[62:65]
	v_mfma_f32_16x16x32_bf16 v[58:61], v[160:163], v[210:213], v[58:61]
	v_mfma_f32_16x16x32_bf16 v[54:57], v[152:155], v[218:221], v[54:57]
	v_mfma_f32_16x16x32_bf16 v[50:53], v[160:163], v[218:221], v[50:53]
	v_mfma_f32_16x16x32_bf16 v[38:41], v[152:155], v[226:229], v[38:41]
	v_mfma_f32_16x16x32_bf16 v[34:37], v[160:163], v[226:229], v[34:37]
	v_mfma_f32_16x16x32_bf16 v[20:23], v[152:155], v[234:237], v[20:23]
	v_mfma_f32_16x16x32_bf16 v[16:19], v[160:163], v[234:237], v[16:19]
	v_mfma_f32_16x16x32_bf16 v[46:49], v[164:167], v[206:209], v[46:49]
	v_mfma_f32_16x16x32_bf16 v[42:45], v[198:201], v[206:209], v[42:45]
	v_mfma_f32_16x16x32_bf16 v[28:31], v[164:167], v[214:217], v[28:31]
	v_mfma_f32_16x16x32_bf16 v[24:27], v[198:201], v[214:217], v[24:27]
	v_mfma_f32_16x16x32_bf16 v[12:15], v[164:167], v[222:225], v[12:15]
	v_mfma_f32_16x16x32_bf16 v[8:11], v[198:201], v[222:225], v[8:11]
	v_mfma_f32_16x16x32_bf16 v[4:7], v[164:167], v[230:233], v[4:7]
	v_mfma_f32_16x16x32_bf16 v[0:3], v[198:201], v[230:233], v[0:3]
	v_mfma_f32_16x16x32_bf16 v[46:49], v[194:197], v[210:213], v[46:49]
	v_mfma_f32_16x16x32_bf16 v[42:45], v[202:205], v[210:213], v[42:45]
	v_mfma_f32_16x16x32_bf16 v[28:31], v[194:197], v[218:221], v[28:31]
	v_mfma_f32_16x16x32_bf16 v[24:27], v[202:205], v[218:221], v[24:27]
	v_mfma_f32_16x16x32_bf16 v[12:15], v[194:197], v[226:229], v[12:15]
	v_mfma_f32_16x16x32_bf16 v[8:11], v[202:205], v[226:229], v[8:11]
	v_mfma_f32_16x16x32_bf16 v[4:7], v[194:197], v[234:237], v[4:7]
	v_mfma_f32_16x16x32_bf16 v[0:3], v[202:205], v[234:237], v[0:3]
	s_barrier
	s_add_i32 s95, 0, 0x18000
	s_add_i32 s96, 0, 0x1c000
	v_add_u32_e32 v160, s95, v139
	v_add_u32_e32 v181, s96, v139
	ds_read_b128 v[148:151], v160
	ds_read_b128 v[152:155], v160 offset:1024
	ds_read_b128 v[156:159], v160 offset:2048
	ds_read_b128 v[160:163], v160 offset:3072
	ds_read_b128 v[164:167], v181
	ds_read_b128 v[194:197], v181 offset:1024
	ds_read_b128 v[198:201], v181 offset:2048
	ds_read_b128 v[202:205], v181 offset:3072
	s_add_u32 s0, s76, s66
	s_addc_u32 s1, s77, s67
	s_mov_b32 m0, s55
	v_lshl_add_u64 v[248:249], s[0:1], 0, v[140:141]
	ds_read_b128 v[206:209], v147 offset:32768
	ds_read_b128 v[210:213], v147 offset:33792
	ds_read_b128 v[214:217], v147 offset:34816
	ds_read_b128 v[218:221], v147 offset:35840
	ds_read_b128 v[222:225], v147 offset:36864
	ds_read_b128 v[226:229], v147 offset:37888
	ds_read_b128 v[230:233], v147 offset:38912
	ds_read_b128 v[234:237], v147 offset:39936
	global_load_lds_dwordx4 v[248:249], off
	v_lshl_add_u64 v[248:249], s[0:1], 0, v[142:143]
	s_mov_b32 m0, s56
	s_nop 0
	global_load_lds_dwordx4 v[248:249], off
	s_waitcnt vmcnt(8)
	s_waitcnt lgkmcnt(0)
	s_barrier
	v_mfma_f32_16x16x32_bf16 v[126:129], v[148:151], v[206:209], v[126:129]
	v_mfma_f32_16x16x32_bf16 v[122:125], v[156:159], v[206:209], v[122:125]
	v_mfma_f32_16x16x32_bf16 v[118:121], v[148:151], v[214:217], v[118:121]
	v_mfma_f32_16x16x32_bf16 v[114:117], v[156:159], v[214:217], v[114:117]
	v_mfma_f32_16x16x32_bf16 v[102:105], v[148:151], v[222:225], v[102:105]
	v_mfma_f32_16x16x32_bf16 v[98:101], v[156:159], v[222:225], v[98:101]
	v_mfma_f32_16x16x32_bf16 v[86:89], v[148:151], v[230:233], v[86:89]
	v_mfma_f32_16x16x32_bf16 v[82:85], v[156:159], v[230:233], v[82:85]
	v_mfma_f32_16x16x32_bf16 v[126:129], v[152:155], v[210:213], v[126:129]
	v_mfma_f32_16x16x32_bf16 v[122:125], v[160:163], v[210:213], v[122:125]
	v_mfma_f32_16x16x32_bf16 v[118:121], v[152:155], v[218:221], v[118:121]
	v_mfma_f32_16x16x32_bf16 v[114:117], v[160:163], v[218:221], v[114:117]
	v_mfma_f32_16x16x32_bf16 v[102:105], v[152:155], v[226:229], v[102:105]
	v_mfma_f32_16x16x32_bf16 v[98:101], v[160:163], v[226:229], v[98:101]
	v_mfma_f32_16x16x32_bf16 v[86:89], v[152:155], v[234:237], v[86:89]
	v_mfma_f32_16x16x32_bf16 v[82:85], v[160:163], v[234:237], v[82:85]
	v_mfma_f32_16x16x32_bf16 v[110:113], v[164:167], v[206:209], v[110:113]
	v_mfma_f32_16x16x32_bf16 v[106:109], v[198:201], v[206:209], v[106:109]
	v_mfma_f32_16x16x32_bf16 v[94:97], v[164:167], v[214:217], v[94:97]
	v_mfma_f32_16x16x32_bf16 v[90:93], v[198:201], v[214:217], v[90:93]
	v_mfma_f32_16x16x32_bf16 v[78:81], v[164:167], v[222:225], v[78:81]
	v_mfma_f32_16x16x32_bf16 v[74:77], v[198:201], v[222:225], v[74:77]
	v_mfma_f32_16x16x32_bf16 v[70:73], v[164:167], v[230:233], v[70:73]
	v_mfma_f32_16x16x32_bf16 v[66:69], v[198:201], v[230:233], v[66:69]
	v_mfma_f32_16x16x32_bf16 v[110:113], v[194:197], v[210:213], v[110:113]
	v_mfma_f32_16x16x32_bf16 v[106:109], v[202:205], v[210:213], v[106:109]
	v_mfma_f32_16x16x32_bf16 v[94:97], v[194:197], v[218:221], v[94:97]
	v_mfma_f32_16x16x32_bf16 v[90:93], v[202:205], v[218:221], v[90:93]
	v_mfma_f32_16x16x32_bf16 v[78:81], v[194:197], v[226:229], v[78:81]
	v_mfma_f32_16x16x32_bf16 v[74:77], v[202:205], v[226:229], v[74:77]
	v_mfma_f32_16x16x32_bf16 v[70:73], v[194:197], v[234:237], v[70:73]
	v_mfma_f32_16x16x32_bf16 v[66:69], v[202:205], v[234:237], v[66:69]
	s_barrier
	s_add_i32 s0, s95, s23
	v_lshl_add_u64 v[168:169], v[168:169], 0, s[26:27]
	s_mov_b32 m0, s0
	ds_read_b128 v[206:209], v147 offset:49152
	ds_read_b128 v[210:213], v147 offset:50176
	ds_read_b128 v[214:217], v147 offset:51200
	ds_read_b128 v[218:221], v147 offset:52224
	ds_read_b128 v[222:225], v147 offset:53248
	ds_read_b128 v[226:229], v147 offset:54272
	ds_read_b128 v[230:233], v147 offset:55296
	ds_read_b128 v[234:237], v147 offset:56320
	global_load_lds_dwordx4 v[168:169], off
	v_lshl_add_u64 v[168:169], v[238:239], 0, s[26:27]
	s_add_i32 m0, s0, 0x2000
	s_add_i32 s0, s96, s23
	global_load_lds_dwordx4 v[168:169], off
	v_lshl_add_u64 v[168:169], v[240:241], 0, s[26:27]
	s_mov_b32 m0, s0
	s_nop 0
	global_load_lds_dwordx4 v[168:169], off
	v_lshl_add_u64 v[168:169], v[242:243], 0, s[26:27]
	s_add_i32 m0, s0, 0x2000
	s_nop 0
	global_load_lds_dwordx4 v[168:169], off
	v_lshl_add_u64 v[168:169], v[244:245], 0, s[26:27]
	s_mov_b32 m0, s57
	s_nop 0
	global_load_lds_dwordx4 v[168:169], off
	v_lshl_add_u64 v[168:169], v[246:247], 0, s[26:27]
	s_mov_b32 m0, s78
	s_nop 0
	global_load_lds_dwordx4 v[168:169], off
	s_waitcnt vmcnt(8)
	s_waitcnt lgkmcnt(0)
	s_barrier
	v_mfma_f32_16x16x32_bf16 v[62:65], v[148:151], v[206:209], v[62:65]
	v_mfma_f32_16x16x32_bf16 v[58:61], v[156:159], v[206:209], v[58:61]
	v_mfma_f32_16x16x32_bf16 v[54:57], v[148:151], v[214:217], v[54:57]
	v_mfma_f32_16x16x32_bf16 v[50:53], v[156:159], v[214:217], v[50:53]
	v_mfma_f32_16x16x32_bf16 v[38:41], v[148:151], v[222:225], v[38:41]
	v_mfma_f32_16x16x32_bf16 v[34:37], v[156:159], v[222:225], v[34:37]
	v_mfma_f32_16x16x32_bf16 v[20:23], v[148:151], v[230:233], v[20:23]
	v_mfma_f32_16x16x32_bf16 v[16:19], v[156:159], v[230:233], v[16:19]
	v_mfma_f32_16x16x32_bf16 v[62:65], v[152:155], v[210:213], v[62:65]
	v_mfma_f32_16x16x32_bf16 v[58:61], v[160:163], v[210:213], v[58:61]
	v_mfma_f32_16x16x32_bf16 v[54:57], v[152:155], v[218:221], v[54:57]
	v_mfma_f32_16x16x32_bf16 v[50:53], v[160:163], v[218:221], v[50:53]
	v_mfma_f32_16x16x32_bf16 v[38:41], v[152:155], v[226:229], v[38:41]
	v_mfma_f32_16x16x32_bf16 v[34:37], v[160:163], v[226:229], v[34:37]
	v_mfma_f32_16x16x32_bf16 v[20:23], v[152:155], v[234:237], v[20:23]
	v_mfma_f32_16x16x32_bf16 v[16:19], v[160:163], v[234:237], v[16:19]
	v_mfma_f32_16x16x32_bf16 v[46:49], v[164:167], v[206:209], v[46:49]
	v_mfma_f32_16x16x32_bf16 v[42:45], v[198:201], v[206:209], v[42:45]
	v_mfma_f32_16x16x32_bf16 v[28:31], v[164:167], v[214:217], v[28:31]
	v_mfma_f32_16x16x32_bf16 v[24:27], v[198:201], v[214:217], v[24:27]
	v_mfma_f32_16x16x32_bf16 v[12:15], v[164:167], v[222:225], v[12:15]
	v_mfma_f32_16x16x32_bf16 v[8:11], v[198:201], v[222:225], v[8:11]
	v_mfma_f32_16x16x32_bf16 v[4:7], v[164:167], v[230:233], v[4:7]
	v_mfma_f32_16x16x32_bf16 v[0:3], v[198:201], v[230:233], v[0:3]
	v_mfma_f32_16x16x32_bf16 v[46:49], v[194:197], v[210:213], v[46:49]
	v_mfma_f32_16x16x32_bf16 v[42:45], v[202:205], v[210:213], v[42:45]
	v_mfma_f32_16x16x32_bf16 v[28:31], v[194:197], v[218:221], v[28:31]
	v_mfma_f32_16x16x32_bf16 v[24:27], v[202:205], v[218:221], v[24:27]
	v_mfma_f32_16x16x32_bf16 v[12:15], v[194:197], v[226:229], v[12:15]
	v_mfma_f32_16x16x32_bf16 v[8:11], v[202:205], v[226:229], v[8:11]
	v_mfma_f32_16x16x32_bf16 v[4:7], v[194:197], v[234:237], v[4:7]
	v_mfma_f32_16x16x32_bf16 v[0:3], v[202:205], v[234:237], v[0:3]
	s_barrier
	s_add_u32 s74, s74, 0x100
	s_addc_u32 s75, s75, 0
	s_add_u32 s85, s85, 0x100
	s_addc_u32 s90, s90, 0
	s_cmp_ge_i32 s91, s94
	s_mov_b32 s76, s91
	s_cbranch_scc0 .LBB0_356
	s_and_b64 vcc, exec, s[72:73]
	s_cbranch_vccz .LBB0_359
	s_barrier
